# EpiRes residual stores made write-through (sc1) so the grid barrier's L2 write-back finds little dirty data (on top of v16)
# speedup vs baseline: 1.0044x; 1.0044x over previous
.LBB0_1025:
	s_sub_i32 s0, s13, 64
	s_ashr_i32 s1, s13, 31
	s_cmp_lt_i32 s13, 64
	s_cselect_b32 s1, s1, 0
	s_cselect_b32 s0, s13, s0
	s_movk_i32 s5, 0x4800
	s_cselect_b32 s2, s79, s97
	s_cselect_b32 s3, s78, s96
	s_cselect_b32 s5, 0x2400, s5
	s_lshl_b64 s[0:1], s[0:1], 20
	s_add_u32 s0, s3, s0
	s_addc_u32 s1, s2, s1
	s_cmp_gt_i32 s13, 31
	s_cselect_b32 s2, s5, 0
	s_lshl_b32 s2, s2, 2
	v_readlane_b32 s3, v254, 45
	v_lshl_or_b32 v152, s12, 8, v157
	s_add_u32 s2, s3, s2
	v_readlane_b32 s3, v254, 47
	v_ashrrev_i32_e32 v153, 31, v152
	s_addc_u32 s3, s3, 0
	v_lshlrev_b64 v[152:153], 2, v[152:153]
	v_add_u32_e32 v154, 0x5000, v152
	global_load_dwordx4 v[160:163], v154, s[2:3]
	global_load_dwordx4 v[164:167], v154, s[2:3] offset:64
	global_load_dwordx4 v[168:171], v154, s[2:3] offset:512
	global_load_dwordx4 v[172:175], v154, s[2:3] offset:576
	v_add_u32_e32 v159, v152, v132
	v_add_u32_e32 v153, v152, v136
	v_add_u32_e32 v196, v152, v138
	v_add_u32_e32 v197, v152, v140
	v_add_u32_e32 v234, v152, v134
	v_add_u32_e32 v235, v152, v142
	v_add_u32_e32 v210, v152, v144
	v_add_u32_e32 v211, v152, v146
	global_load_dwordx4 v[176:179], v159, s[0:1]
	global_load_dwordx4 v[180:183], v153, s[0:1]
	global_load_dwordx4 v[184:187], v196, s[0:1]
	global_load_dwordx4 v[188:191], v197, s[0:1]
	global_load_dwordx4 v[192:195], v234, s[0:1]
	global_load_dwordx4 v[214:217], v235, s[0:1]
	global_load_dwordx4 v[218:221], v210, s[0:1]
	global_load_dwordx4 v[222:225], v211, s[0:1]
	global_load_dwordx4 v[226:229], v159, s[0:1] offset:64
	global_load_dwordx4 v[230:233], v153, s[0:1] offset:64
	global_load_dwordx4 v[240:243], v196, s[0:1] offset:64
	global_load_dwordx4 v[244:247], v197, s[0:1] offset:64
	v_readlane_b32 s18, v249, 56
	s_mov_b64 s[2:3], -1
	s_andn2_b64 vcc, exec, s[38:39]
	v_readlane_b32 s19, v249, 57
	s_waitcnt vmcnt(11)
	v_pk_fma_f32 v[128:129], v[128:129], v[162:163], v[178:179]
	v_pk_fma_f32 v[126:127], v[126:127], v[160:161], v[176:177]
	global_store_dwordx4 v159, v[126:129], s[0:1] sc1
	s_nop 1
	global_load_dwordx4 v[126:129], v234, s[0:1] offset:64
	s_waitcnt vmcnt(12)
	v_pk_fma_f32 v[124:125], v[124:125], v[162:163], v[182:183]
	v_pk_fma_f32 v[122:123], v[122:123], v[160:161], v[180:181]
	global_store_dwordx4 v153, v[122:125], s[0:1] sc1
	s_nop 1
	global_load_dwordx4 v[122:125], v235, s[0:1] offset:64
	s_waitcnt vmcnt(13)
	v_pk_fma_f32 v[120:121], v[120:121], v[162:163], v[186:187]
	v_pk_fma_f32 v[118:119], v[118:119], v[160:161], v[184:185]
	global_store_dwordx4 v196, v[118:121], s[0:1] sc1
	s_nop 1
	global_load_dwordx4 v[118:121], v210, s[0:1] offset:64
	s_waitcnt vmcnt(14)
	v_pk_fma_f32 v[116:117], v[116:117], v[162:163], v[190:191]
	v_pk_fma_f32 v[114:115], v[114:115], v[160:161], v[188:189]
	global_store_dwordx4 v197, v[114:117], s[0:1] sc1
	s_nop 1
	global_load_dwordx4 v[114:117], v211, s[0:1] offset:64
	s_waitcnt vmcnt(15)
	v_pk_fma_f32 v[112:113], v[112:113], v[162:163], v[194:195]
	v_pk_fma_f32 v[110:111], v[110:111], v[160:161], v[192:193]
	global_store_dwordx4 v234, v[110:113], s[0:1] sc1
	s_nop 1
	global_load_dwordx4 v[110:113], v159, s[0:1] offset:512
	s_waitcnt vmcnt(16)
	v_pk_fma_f32 v[108:109], v[108:109], v[162:163], v[216:217]
	v_pk_fma_f32 v[106:107], v[106:107], v[160:161], v[214:215]
	global_store_dwordx4 v235, v[106:109], s[0:1] sc1
	s_nop 1
	global_load_dwordx4 v[106:109], v153, s[0:1] offset:512
	s_waitcnt vmcnt(17)
	v_pk_fma_f32 v[100:101], v[100:101], v[162:163], v[220:221]
	v_pk_fma_f32 v[98:99], v[98:99], v[160:161], v[218:219]
	global_store_dwordx4 v210, v[98:101], s[0:1] sc1
	s_nop 1
	global_load_dwordx4 v[98:101], v196, s[0:1] offset:512
	s_waitcnt vmcnt(18)
	v_pk_fma_f32 v[96:97], v[96:97], v[162:163], v[224:225]
	v_pk_fma_f32 v[94:95], v[94:95], v[160:161], v[222:223]
	global_store_dwordx4 v211, v[94:97], s[0:1] sc1
	s_nop 1
	global_load_dwordx4 v[94:97], v197, s[0:1] offset:512
	s_waitcnt vmcnt(19)
	v_pk_fma_f32 v[104:105], v[104:105], v[166:167], v[228:229]
	v_pk_fma_f32 v[102:103], v[102:103], v[164:165], v[226:227]
	global_store_dwordx4 v159, v[102:105], s[0:1] offset:64 sc1
	s_nop 1
	global_load_dwordx4 v[102:105], v234, s[0:1] offset:512
	s_waitcnt vmcnt(20)
	v_pk_fma_f32 v[92:93], v[92:93], v[166:167], v[232:233]
	v_pk_fma_f32 v[90:91], v[90:91], v[164:165], v[230:231]
	global_store_dwordx4 v153, v[90:93], s[0:1] offset:64 sc1
	s_nop 1
	global_load_dwordx4 v[90:93], v235, s[0:1] offset:512
	s_waitcnt vmcnt(21)
	v_pk_fma_f32 v[88:89], v[88:89], v[166:167], v[242:243]
	v_pk_fma_f32 v[86:87], v[86:87], v[164:165], v[240:241]
	global_store_dwordx4 v196, v[86:89], s[0:1] offset:64 sc1
	s_nop 1
	global_load_dwordx4 v[86:89], v210, s[0:1] offset:512
	s_waitcnt vmcnt(22)
	v_pk_fma_f32 v[84:85], v[84:85], v[166:167], v[246:247]
	v_pk_fma_f32 v[82:83], v[82:83], v[164:165], v[244:245]
	global_store_dwordx4 v197, v[82:85], s[0:1] offset:64 sc1
	s_nop 1
	global_load_dwordx4 v[82:85], v211, s[0:1] offset:512
	s_waitcnt vmcnt(22)
	v_pk_fma_f32 v[80:81], v[80:81], v[166:167], v[128:129]
	v_pk_fma_f32 v[78:79], v[78:79], v[164:165], v[126:127]
	global_store_dwordx4 v234, v[78:81], s[0:1] offset:64 sc1
	s_nop 1
	global_load_dwordx4 v[78:81], v159, s[0:1] offset:576
	s_waitcnt vmcnt(22)
	v_pk_fma_f32 v[76:77], v[76:77], v[166:167], v[124:125]
	v_pk_fma_f32 v[74:75], v[74:75], v[164:165], v[122:123]
	global_store_dwordx4 v235, v[74:77], s[0:1] offset:64 sc1
	s_nop 1
	global_load_dwordx4 v[74:77], v153, s[0:1] offset:576
	s_waitcnt vmcnt(22)
	v_pk_fma_f32 v[72:73], v[72:73], v[166:167], v[120:121]
	v_pk_fma_f32 v[70:71], v[70:71], v[164:165], v[118:119]
	global_store_dwordx4 v210, v[70:73], s[0:1] offset:64 sc1
	s_nop 1
	global_load_dwordx4 v[70:73], v196, s[0:1] offset:576
	s_waitcnt vmcnt(22)
	v_pk_fma_f32 v[68:69], v[68:69], v[166:167], v[116:117]
	v_pk_fma_f32 v[66:67], v[66:67], v[164:165], v[114:115]
	global_store_dwordx4 v211, v[66:69], s[0:1] offset:64 sc1
	s_nop 1
	global_load_dwordx4 v[66:69], v197, s[0:1] offset:576
	s_waitcnt vmcnt(22)
	v_pk_fma_f32 v[64:65], v[64:65], v[170:171], v[112:113]
	v_pk_fma_f32 v[62:63], v[62:63], v[168:169], v[110:111]
	global_store_dwordx4 v159, v[62:65], s[0:1] offset:512 sc1
	s_nop 1
	global_load_dwordx4 v[62:65], v234, s[0:1] offset:576
	s_waitcnt vmcnt(22)
	v_pk_fma_f32 v[60:61], v[60:61], v[170:171], v[108:109]
	v_pk_fma_f32 v[58:59], v[58:59], v[168:169], v[106:107]
	global_store_dwordx4 v153, v[58:61], s[0:1] offset:512 sc1
	s_nop 1
	global_load_dwordx4 v[58:61], v235, s[0:1] offset:576
	s_waitcnt vmcnt(22)
	v_pk_fma_f32 v[56:57], v[56:57], v[170:171], v[100:101]
	v_pk_fma_f32 v[54:55], v[54:55], v[168:169], v[98:99]
	global_store_dwordx4 v196, v[54:57], s[0:1] offset:512 sc1
	s_nop 1
	global_load_dwordx4 v[54:57], v210, s[0:1] offset:576
	s_waitcnt vmcnt(22)
	v_pk_fma_f32 v[52:53], v[52:53], v[170:171], v[96:97]
	v_pk_fma_f32 v[50:51], v[50:51], v[168:169], v[94:95]
	global_store_dwordx4 v197, v[50:53], s[0:1] offset:512 sc1
	s_nop 1
	global_load_dwordx4 v[50:53], v211, s[0:1] offset:576
	s_waitcnt vmcnt(22)
	v_pk_fma_f32 v[48:49], v[48:49], v[170:171], v[104:105]
	v_pk_fma_f32 v[46:47], v[46:47], v[168:169], v[102:103]
	global_store_dwordx4 v234, v[46:49], s[0:1] offset:512 sc1
	s_waitcnt vmcnt(21)
	v_pk_fma_f32 v[44:45], v[44:45], v[170:171], v[92:93]
	v_pk_fma_f32 v[42:43], v[42:43], v[168:169], v[90:91]
	global_store_dwordx4 v235, v[42:45], s[0:1] offset:512 sc1
	s_waitcnt vmcnt(20)
	v_pk_fma_f32 v[36:37], v[36:37], v[170:171], v[88:89]
	v_pk_fma_f32 v[34:35], v[34:35], v[168:169], v[86:87]
	global_store_dwordx4 v210, v[34:37], s[0:1] offset:512 sc1
	s_waitcnt vmcnt(19)
	v_pk_fma_f32 v[32:33], v[32:33], v[170:171], v[84:85]
	v_pk_fma_f32 v[30:31], v[30:31], v[168:169], v[82:83]
	global_store_dwordx4 v211, v[30:33], s[0:1] offset:512 sc1
	s_waitcnt vmcnt(18)
	v_pk_fma_f32 v[40:41], v[40:41], v[174:175], v[80:81]
	v_pk_fma_f32 v[38:39], v[38:39], v[172:173], v[78:79]
	global_store_dwordx4 v159, v[38:41], s[0:1] offset:576 sc1
	s_waitcnt vmcnt(17)
	v_pk_fma_f32 v[28:29], v[28:29], v[174:175], v[76:77]
	v_pk_fma_f32 v[26:27], v[26:27], v[172:173], v[74:75]
	global_store_dwordx4 v153, v[26:29], s[0:1] offset:576 sc1
	s_waitcnt vmcnt(16)
	v_pk_fma_f32 v[24:25], v[24:25], v[174:175], v[72:73]
	v_pk_fma_f32 v[22:23], v[22:23], v[172:173], v[70:71]
	global_store_dwordx4 v196, v[22:25], s[0:1] offset:576 sc1
	s_waitcnt vmcnt(15)
	v_pk_fma_f32 v[20:21], v[20:21], v[174:175], v[68:69]
	v_pk_fma_f32 v[18:19], v[18:19], v[172:173], v[66:67]
	global_store_dwordx4 v197, v[18:21], s[0:1] offset:576 sc1
	s_waitcnt vmcnt(14)
	v_pk_fma_f32 v[16:17], v[16:17], v[174:175], v[64:65]
	v_pk_fma_f32 v[14:15], v[14:15], v[172:173], v[62:63]
	global_store_dwordx4 v234, v[14:17], s[0:1] offset:576 sc1
	s_waitcnt vmcnt(13)
	v_pk_fma_f32 v[12:13], v[12:13], v[174:175], v[60:61]
	v_pk_fma_f32 v[10:11], v[10:11], v[172:173], v[58:59]
	global_store_dwordx4 v235, v[10:13], s[0:1] offset:576 sc1
	s_waitcnt vmcnt(12)
	v_pk_fma_f32 v[8:9], v[8:9], v[174:175], v[56:57]
	v_pk_fma_f32 v[6:7], v[6:7], v[172:173], v[54:55]
	global_store_dwordx4 v210, v[6:9], s[0:1] offset:576 sc1
	s_waitcnt vmcnt(11)
	v_pk_fma_f32 v[4:5], v[4:5], v[174:175], v[52:53]
	v_pk_fma_f32 v[2:3], v[2:3], v[172:173], v[50:51]
	global_store_dwordx4 v211, v[2:5], s[0:1] offset:576 sc1
	s_cbranch_vccnz .LBB0_1014
	s_andn2_b64 vcc, exec, s[40:41]
	s_cbranch_vccnz .LBB0_1013
	s_barrier
	s_branch .LBB0_1013

.LBB0_1250:
	s_sub_i32 s0, s37, 64
	s_ashr_i32 s1, s37, 31
	s_cmp_lt_i32 s37, 64
	s_cselect_b32 s1, s1, 0
	s_cselect_b32 s0, s37, s0
	s_movk_i32 s8, 0x4800
	s_cselect_b32 s2, s79, s97
	s_cselect_b32 s3, s78, s96
	s_cselect_b32 s8, 0x2400, s8
	s_lshl_b64 s[0:1], s[0:1], 20
	s_add_u32 s0, s3, s0
	s_addc_u32 s1, s2, s1
	s_cmp_gt_i32 s37, 31
	s_cselect_b32 s2, s8, 0
	s_lshl_b32 s2, s2, 2
	v_lshl_or_b32 v152, s36, 8, v157
	s_add_u32 s2, s29, s2
	v_ashrrev_i32_e32 v153, 31, v152
	s_addc_u32 s3, s30, 0
	v_lshlrev_b64 v[152:153], 2, v[152:153]
	global_load_dwordx4 v[160:163], v152, s[2:3]
	global_load_dwordx4 v[164:167], v152, s[2:3] offset:64
	global_load_dwordx4 v[168:171], v152, s[2:3] offset:512
	global_load_dwordx4 v[172:175], v152, s[2:3] offset:576
	v_add_u32_e32 v159, v152, v132
	v_add_u32_e32 v153, v152, v136
	v_add_u32_e32 v196, v152, v138
	v_add_u32_e32 v197, v152, v140
	v_add_u32_e32 v234, v152, v134
	v_add_u32_e32 v235, v152, v142
	v_add_u32_e32 v210, v152, v144
	v_add_u32_e32 v211, v152, v146
	global_load_dwordx4 v[176:179], v159, s[0:1]
	global_load_dwordx4 v[180:183], v153, s[0:1]
	global_load_dwordx4 v[184:187], v196, s[0:1]
	global_load_dwordx4 v[188:191], v197, s[0:1]
	global_load_dwordx4 v[192:195], v234, s[0:1]
	global_load_dwordx4 v[214:217], v235, s[0:1]
	global_load_dwordx4 v[218:221], v210, s[0:1]
	global_load_dwordx4 v[222:225], v211, s[0:1]
	global_load_dwordx4 v[226:229], v159, s[0:1] offset:64
	global_load_dwordx4 v[230:233], v153, s[0:1] offset:64
	global_load_dwordx4 v[240:243], v196, s[0:1] offset:64
	global_load_dwordx4 v[244:247], v197, s[0:1] offset:64
	v_readlane_b32 s18, v249, 56
	s_mov_b64 s[2:3], -1
	s_and_b64 vcc, exec, s[38:39]
	v_readlane_b32 s19, v249, 57
	s_waitcnt vmcnt(11)
	v_pk_mul_f32 v[160:161], v[160:161], 0.5 op_sel_hi:[1,0]
	v_pk_mul_f32 v[162:163], v[162:163], 0.5 op_sel_hi:[1,0]
	v_pk_fma_f32 v[128:129], v[128:129], v[162:163], v[178:179]
	v_pk_fma_f32 v[126:127], v[126:127], v[160:161], v[176:177]
	global_store_dwordx4 v159, v[126:129], s[0:1] sc1
	s_nop 1
	global_load_dwordx4 v[126:129], v234, s[0:1] offset:64
	s_waitcnt vmcnt(12)
	v_pk_fma_f32 v[124:125], v[124:125], v[162:163], v[182:183]
	v_pk_fma_f32 v[122:123], v[122:123], v[160:161], v[180:181]
	global_store_dwordx4 v153, v[122:125], s[0:1] sc1
	s_nop 1
	global_load_dwordx4 v[122:125], v235, s[0:1] offset:64
	s_waitcnt vmcnt(13)
	v_pk_fma_f32 v[120:121], v[120:121], v[162:163], v[186:187]
	v_pk_fma_f32 v[118:119], v[118:119], v[160:161], v[184:185]
	global_store_dwordx4 v196, v[118:121], s[0:1] sc1
	s_nop 1
	global_load_dwordx4 v[118:121], v210, s[0:1] offset:64
	s_waitcnt vmcnt(14)
	v_pk_fma_f32 v[116:117], v[116:117], v[162:163], v[190:191]
	v_pk_fma_f32 v[114:115], v[114:115], v[160:161], v[188:189]
	global_store_dwordx4 v197, v[114:117], s[0:1] sc1
	s_nop 1
	global_load_dwordx4 v[114:117], v211, s[0:1] offset:64
	s_waitcnt vmcnt(15)
	v_pk_fma_f32 v[112:113], v[112:113], v[162:163], v[194:195]
	v_pk_fma_f32 v[110:111], v[110:111], v[160:161], v[192:193]
	global_store_dwordx4 v234, v[110:113], s[0:1] sc1
	s_nop 1
	global_load_dwordx4 v[110:113], v159, s[0:1] offset:512
	s_waitcnt vmcnt(16)
	v_pk_fma_f32 v[108:109], v[108:109], v[162:163], v[216:217]
	v_pk_fma_f32 v[106:107], v[106:107], v[160:161], v[214:215]
	global_store_dwordx4 v235, v[106:109], s[0:1] sc1
	s_nop 1
	global_load_dwordx4 v[106:109], v153, s[0:1] offset:512
	s_waitcnt vmcnt(17)
	v_pk_fma_f32 v[104:105], v[104:105], v[162:163], v[220:221]
	v_pk_fma_f32 v[102:103], v[102:103], v[160:161], v[218:219]
	global_store_dwordx4 v210, v[102:105], s[0:1] sc1
	s_nop 1
	global_load_dwordx4 v[102:105], v196, s[0:1] offset:512
	s_waitcnt vmcnt(18)
	v_pk_fma_f32 v[96:97], v[96:97], v[162:163], v[224:225]
	v_pk_fma_f32 v[94:95], v[94:95], v[160:161], v[222:223]
	global_store_dwordx4 v211, v[94:97], s[0:1] sc1
	s_nop 1
	global_load_dwordx4 v[94:97], v197, s[0:1] offset:512
	s_waitcnt vmcnt(19)
	v_pk_mul_f32 v[164:165], v[164:165], 0.5 op_sel_hi:[1,0]
	v_pk_mul_f32 v[166:167], v[166:167], 0.5 op_sel_hi:[1,0]
	v_pk_fma_f32 v[100:101], v[100:101], v[166:167], v[228:229]
	v_pk_fma_f32 v[98:99], v[98:99], v[164:165], v[226:227]
	global_store_dwordx4 v159, v[98:101], s[0:1] offset:64 sc1
	s_nop 1
	global_load_dwordx4 v[98:101], v234, s[0:1] offset:512
	s_waitcnt vmcnt(20)
	v_pk_fma_f32 v[92:93], v[92:93], v[166:167], v[232:233]
	v_pk_fma_f32 v[90:91], v[90:91], v[164:165], v[230:231]
	global_store_dwordx4 v153, v[90:93], s[0:1] offset:64 sc1
	s_nop 1
	global_load_dwordx4 v[90:93], v235, s[0:1] offset:512
	s_waitcnt vmcnt(21)
	v_pk_fma_f32 v[88:89], v[88:89], v[166:167], v[242:243]
	v_pk_fma_f32 v[86:87], v[86:87], v[164:165], v[240:241]
	global_store_dwordx4 v196, v[86:89], s[0:1] offset:64 sc1
	s_nop 1
	global_load_dwordx4 v[86:89], v210, s[0:1] offset:512
	s_waitcnt vmcnt(22)
	v_pk_fma_f32 v[84:85], v[84:85], v[166:167], v[246:247]
	v_pk_fma_f32 v[82:83], v[82:83], v[164:165], v[244:245]
	global_store_dwordx4 v197, v[82:85], s[0:1] offset:64 sc1
	s_nop 1
	global_load_dwordx4 v[82:85], v211, s[0:1] offset:512
	s_waitcnt vmcnt(22)
	v_pk_fma_f32 v[80:81], v[80:81], v[166:167], v[128:129]
	v_pk_fma_f32 v[78:79], v[78:79], v[164:165], v[126:127]
	global_store_dwordx4 v234, v[78:81], s[0:1] offset:64 sc1
	s_nop 1
	global_load_dwordx4 v[78:81], v159, s[0:1] offset:576
	s_waitcnt vmcnt(22)
	v_pk_fma_f32 v[76:77], v[76:77], v[166:167], v[124:125]
	v_pk_fma_f32 v[74:75], v[74:75], v[164:165], v[122:123]
	global_store_dwordx4 v235, v[74:77], s[0:1] offset:64 sc1
	s_nop 1
	global_load_dwordx4 v[74:77], v153, s[0:1] offset:576
	s_waitcnt vmcnt(22)
	v_pk_fma_f32 v[72:73], v[72:73], v[166:167], v[120:121]
	v_pk_fma_f32 v[70:71], v[70:71], v[164:165], v[118:119]
	global_store_dwordx4 v210, v[70:73], s[0:1] offset:64 sc1
	s_nop 1
	global_load_dwordx4 v[70:73], v196, s[0:1] offset:576
	s_waitcnt vmcnt(22)
	v_pk_fma_f32 v[64:65], v[64:65], v[166:167], v[116:117]
	v_pk_fma_f32 v[62:63], v[62:63], v[164:165], v[114:115]
	global_store_dwordx4 v211, v[62:65], s[0:1] offset:64 sc1
	s_nop 1
	global_load_dwordx4 v[62:65], v197, s[0:1] offset:576
	s_waitcnt vmcnt(22)
	v_pk_mul_f32 v[168:169], v[168:169], 0.5 op_sel_hi:[1,0]
	v_pk_mul_f32 v[170:171], v[170:171], 0.5 op_sel_hi:[1,0]
	v_pk_fma_f32 v[68:69], v[68:69], v[170:171], v[112:113]
	v_pk_fma_f32 v[66:67], v[66:67], v[168:169], v[110:111]
	global_store_dwordx4 v159, v[66:69], s[0:1] offset:512 sc1
	s_nop 1
	global_load_dwordx4 v[66:69], v234, s[0:1] offset:576
	s_waitcnt vmcnt(22)
	v_pk_fma_f32 v[60:61], v[60:61], v[170:171], v[108:109]
	v_pk_fma_f32 v[58:59], v[58:59], v[168:169], v[106:107]
	global_store_dwordx4 v153, v[58:61], s[0:1] offset:512 sc1
	s_nop 1
	global_load_dwordx4 v[58:61], v235, s[0:1] offset:576
	s_waitcnt vmcnt(22)
	v_pk_fma_f32 v[56:57], v[56:57], v[170:171], v[104:105]
	v_pk_fma_f32 v[54:55], v[54:55], v[168:169], v[102:103]
	global_store_dwordx4 v196, v[54:57], s[0:1] offset:512 sc1
	s_nop 1
	global_load_dwordx4 v[54:57], v210, s[0:1] offset:576
	s_waitcnt vmcnt(22)
	v_pk_fma_f32 v[52:53], v[52:53], v[170:171], v[96:97]
	v_pk_fma_f32 v[50:51], v[50:51], v[168:169], v[94:95]
	global_store_dwordx4 v197, v[50:53], s[0:1] offset:512 sc1
	s_nop 1
	global_load_dwordx4 v[50:53], v211, s[0:1] offset:576
	s_waitcnt vmcnt(22)
	v_pk_fma_f32 v[48:49], v[48:49], v[170:171], v[100:101]
	v_pk_fma_f32 v[46:47], v[46:47], v[168:169], v[98:99]
	global_store_dwordx4 v234, v[46:49], s[0:1] offset:512 sc1
	s_waitcnt vmcnt(21)
	v_pk_fma_f32 v[44:45], v[44:45], v[170:171], v[92:93]
	v_pk_fma_f32 v[42:43], v[42:43], v[168:169], v[90:91]
	global_store_dwordx4 v235, v[42:45], s[0:1] offset:512 sc1
	s_waitcnt vmcnt(20)
	v_pk_fma_f32 v[40:41], v[40:41], v[170:171], v[88:89]
	v_pk_fma_f32 v[38:39], v[38:39], v[168:169], v[86:87]
	global_store_dwordx4 v210, v[38:41], s[0:1] offset:512 sc1
	s_waitcnt vmcnt(19)
	v_pk_fma_f32 v[32:33], v[32:33], v[170:171], v[84:85]
	v_pk_fma_f32 v[30:31], v[30:31], v[168:169], v[82:83]
	global_store_dwordx4 v211, v[30:33], s[0:1] offset:512 sc1
	s_waitcnt vmcnt(18)
	v_pk_mul_f32 v[172:173], v[172:173], 0.5 op_sel_hi:[1,0]
	v_pk_mul_f32 v[174:175], v[174:175], 0.5 op_sel_hi:[1,0]
	v_pk_fma_f32 v[36:37], v[36:37], v[174:175], v[80:81]
	v_pk_fma_f32 v[34:35], v[34:35], v[172:173], v[78:79]
	global_store_dwordx4 v159, v[34:37], s[0:1] offset:576 sc1
	s_waitcnt vmcnt(17)
	v_pk_fma_f32 v[28:29], v[28:29], v[174:175], v[76:77]
	v_pk_fma_f32 v[26:27], v[26:27], v[172:173], v[74:75]
	global_store_dwordx4 v153, v[26:29], s[0:1] offset:576 sc1
	s_waitcnt vmcnt(16)
	v_pk_fma_f32 v[24:25], v[24:25], v[174:175], v[72:73]
	v_pk_fma_f32 v[22:23], v[22:23], v[172:173], v[70:71]
	global_store_dwordx4 v196, v[22:25], s[0:1] offset:576 sc1
	s_waitcnt vmcnt(15)
	v_pk_fma_f32 v[20:21], v[20:21], v[174:175], v[64:65]
	v_pk_fma_f32 v[18:19], v[18:19], v[172:173], v[62:63]
	global_store_dwordx4 v197, v[18:21], s[0:1] offset:576 sc1
	s_waitcnt vmcnt(14)
	v_pk_fma_f32 v[16:17], v[16:17], v[174:175], v[68:69]
	v_pk_fma_f32 v[14:15], v[14:15], v[172:173], v[66:67]
	global_store_dwordx4 v234, v[14:17], s[0:1] offset:576 sc1
	s_waitcnt vmcnt(13)
	v_pk_fma_f32 v[12:13], v[12:13], v[174:175], v[60:61]
	v_pk_fma_f32 v[10:11], v[10:11], v[172:173], v[58:59]
	global_store_dwordx4 v235, v[10:13], s[0:1] offset:576 sc1
	s_waitcnt vmcnt(12)
	v_pk_fma_f32 v[8:9], v[8:9], v[174:175], v[56:57]
	v_pk_fma_f32 v[6:7], v[6:7], v[172:173], v[54:55]
	global_store_dwordx4 v210, v[6:9], s[0:1] offset:576 sc1
	s_waitcnt vmcnt(11)
	v_pk_fma_f32 v[4:5], v[4:5], v[174:175], v[52:53]
	v_pk_fma_f32 v[2:3], v[2:3], v[172:173], v[50:51]
	global_store_dwordx4 v211, v[2:5], s[0:1] offset:576 sc1
	s_cbranch_vccnz .LBB0_1235
	s_andn2_b64 vcc, exec, s[42:43]
	s_cbranch_vccnz .LBB0_1234
	s_barrier
	s_branch .LBB0_1234
